# v15 + P5: first K-iteration after each epilogue peeled with relaxed counted waits so the epilogue's stores drain under the next tile's MFMAs
# speedup vs baseline: 1.0036x; 1.0036x over previous
; #define PG8_WAIT_V(n) asm volatile("s_waitcnt vmcnt(" #n ")" ::: "memory")
;     __host__ __device__ bool next(int i, Unit& u) const {
;         long L = (long)i * G + c; if (L >= (long)nwg * rep) return false; L %= nwg;
;         int wgid = (int)L; { const int q = nwg / NXCD, r = nwg % NXCD, xcd = wgid % NXCD, off = wgid / NXCD; wgid = (xcd < r ? xcd * (q + 1) : r * (q + 1) + (xcd - r) * q) + off; }
;         const int nig = WGM * nN, gid = wgid / nig, fm = gid * WGM, gsz = (nM - fm) < WGM ? (nM - fm) : WGM;
;         u.pm = fm + ((wgid % nig) % gsz); u.pn = (wgid % nig) / gsz; u.seg = 0; return true;
; template <class Epi, class Sched, bool ALIGN_EPI = false, bool SP2 = false>
; __device__ __forceinline__ void gemm_phase(PG8_LAS unsigned char* lds, const Gemm g, const Sched& S, const Epi& E) {
;     ...
;     for (int i = 0; i < 2; ++i) { int R, C; stage_rc(tid * 16 + i * 8192, R, C); const int Rb = Epi::PERM ? ((R & ~31) + perm32(R & 31)) : R;
;         voffA[i] = (unsigned)(R * K + C) * 2u; voffB[i] = (unsigned)(Rb * K + C) * 2u; }
;     const size_t kstep = (size_t)(BK * 2);
;     const size_t hstep = (size_t)HALF * K * 2;
;     const size_t tstep = 2 * hstep;
;     const unsigned ldsw = (unsigned)wid * 1024u;
;     const int aoff = lds_byte(wr * 64 + fr, fq * 8), boff = lds_byte(wc * 32 + fr, fq * 8);
;     ...
;     Unit cur, nxt; int ui = 0;
;     if (!S.next(0, cur)) return;
;     f32x4 acc[2][2][4][2];
; #pragma unroll
;     for (int a = 0; a < 2; ++a)
; #pragma unroll
;         for (int b = 0; b < 2; ++b)
; #pragma unroll
;             for (int m = 0; m < 4; ++m)
; #pragma unroll
;                 for (int n = 0; n < 2; ++n) acc[a][b][m][n] = (f32x4){0.f, 0.f, 0.f, 0.f};
;     bf16x8 At[4][2], B0[2][2], B1[2][2];
;     const char* cA = (const char*)(cur.seg ? g.A1 : g.A0) + (size_t)cur.pm * tstep; const char* cB = (const char*)(cur.seg ? g.B1 : g.B0) + (size_t)cur.pn * tstep;
;     S.a_ready(cur);
;     if constexpr (SP2) {
;         PG8_STAGE(PG8_SB(0, 0), cB, voffB); PG8_STAGE(PG8_SB(0, 1), cB + hstep, voffB); PG8_STAGE(PG8_SA(0, 0), cA, voffA); PG8_STAGE(PG8_SA(0, 1), cA + hstep, voffA);
;         if (wr == 1) PG8_BAR;
;         PG8_WAIT_V(2); PG8_BAR;
;         PG8_STAGE(PG8_SB(1, 0), cB + kstep, voffB); PG8_STAGE(PG8_SA(1, 0), cA + kstep, voffA); PG8_STAGE(PG8_SB(1, 1), cB + hstep + kstep, voffB);
;         PG8_WAIT_V(6); PG8_BAR;
;     } else {
.LBB0_761:
	s_cmp_lt_i32 s28, 6
	s_cselect_b64 s[0:1], -1, 0
	s_and_b64 s[0:1], s[0:1], s[4:5]
	s_andn2_b64 vcc, exec, s[0:1]
	s_cbranch_vccnz .LBB0_778
	s_cmpk_gt_i32 s2, 0xaff
	v_readfirstlane_b32 s3, v164
	s_cbranch_scc1 .LBB0_778
	s_mov_b32 s66, 0
	v_and_b32_e32 v240, 7, v164
	v_bfe_u32 v241, v164, 4, 3
	v_xor_b32_e32 v240, v240, v241
	v_lshlrev_b32_e32 v240, 4, v240
	v_lshrrev_b32_e32 v241, 3, v164
	v_lshl_or_b32 v242, v241, 11, v240
	v_add_u32_e32 v243, 0x20000, v242
	v_bfe_u32 v244, v164, 5, 2
	v_lshlrev_b32_e32 v244, 3, v244
	v_bfe_u32 v245, v164, 7, 1
	v_lshl_or_b32 v244, v245, 2, v244
	v_bfe_u32 v245, v164, 3, 2
	v_or_b32_e32 v244, v244, v245
	v_bfe_u32 v245, v164, 8, 1
	v_lshl_or_b32 v244, v245, 5, v244
	v_lshl_or_b32 v244, v244, 11, v240
	v_add_u32_e32 v245, 0x20000, v244
	v_and_b32_e32 v246, 15, v164
	v_bfe_u32 v247, v164, 4, 2
	v_bfe_u32 v248, v164, 1, 3
	v_xor_b32_e32 v247, v247, v248
	v_lshlrev_b32_e32 v247, 4, v247
	v_lshl_or_b32 v246, v246, 7, v247
	v_lshrrev_b32_e32 v0, 5, v164
	v_lshrrev_b32_e32 v2, 1, v164
	v_and_b32_e32 v0, 4, v0
	v_bfe_u32 v1, v164, 2, 2
	v_and_b32_e32 v2, 24, v2
	v_or3_b32 v0, v0, v1, v2
	v_lshlrev_b32_e32 v1, 4, v164
	v_add_u32_e32 v8, 0x2000, v1
	v_lshrrev_b32_e32 v2, 7, v8
	s_movk_i32 s4, 0xe0
	v_and_b32_e32 v4, 32, v164
	s_waitcnt lgkmcnt(0)
	v_and_or_b32 v3, v2, s4, v0
	v_bitop3_b32 v9, v1, v4, 48 bitop3:0x6c
	v_and_b32_e32 v10, 64, v164
	v_bfe_u32 v11, v164, 2, 4
	s_movk_i32 s4, 0xf0
	v_or_b32_e32 v1, v9, v10
	v_and_or_b32 v2, v2, s4, v11
	v_mov_b32_e32 v130, v243
	v_lshrrev_b32_e32 v2, 3, v164
	s_movk_i32 s4, 0x60
	v_and_or_b32 v0, v2, s4, v0
	s_movk_i32 s4, 0x70
	v_mov_b32_e32 v132, v244
	v_and_or_b32 v0, v2, s4, v11
	s_mul_hi_i32 s4, s2, 0x2e8ba2e9
	s_lshr_b32 s7, s4, 31
	s_ashr_i32 s4, s4, 9
	s_add_i32 s4, s4, s7
	s_mulk_i32 s4, 0xb00
	s_sub_i32 s4, s2, s4
	s_sext_i32_i16 s7, s4
	s_bfe_u32 s7, s7, 0x3001c
	s_add_i32 s7, s4, s7
	s_sext_i32_i16 s8, s7
	s_and_b32 s7, s7, 0xfff8
	s_lshr_b32 s5, s3, 6
	s_sub_i32 s4, s4, s7
	s_lshr_b32 s16, s3, 8
	s_lshl_b32 s6, s5, 10
	s_ashr_i32 s8, s8, 3
	s_sext_i32_i16 s7, s4
	s_cmp_lt_i32 s7, 0
	s_movk_i32 s7, 0x161
	s_cselect_b32 s9, s7, 0x160
	s_mul_i32 s4, s4, s9
	s_add_i32 s4, s4, s8
	s_sext_i32_i16 s8, s4
	s_mulk_i32 s8, 0xba3
	s_lshr_b32 s9, s8, 31
	s_ashr_i32 s8, s8, 19
	s_add_i32 s8, s8, s9
	s_lshl_b32 s9, s8, 3
	s_mulk_i32 s8, 0xb0
	s_sub_i32 s8, s4, s8
	s_sext_i32_i16 s4, s8
	s_bfe_u32 s4, s4, 0x3001c
	s_add_i32 s14, s8, s4
	s_sext_i32_i16 s4, s14
	s_and_b32 s14, s14, 0xfff8
	s_sub_i32 s8, s8, s14
	s_sext_i32_i16 s8, s8
	s_lshr_b32 s4, s4, 3
	s_add_i32 s36, s9, s8
	s_ashr_i32 s37, s36, 31
	s_bfe_i64 s[8:9], s[4:5], 0x100000
	s_lshl_b64 s[14:15], s[36:37], 19
	s_lshl_b64 s[8:9], s[8:9], 19
	s_add_u32 s40, s60, s8
	s_addc_u32 s41, s61, s9
	s_add_i32 s8, s6, 0
	s_add_i32 m0, s8, 0x10000
	v_mov_b32_e32 v128, v245
	global_load_lds_dwordx4 v132, s[40:41]
	s_add_i32 m0, s8, 0x12000
	s_add_u32 s18, s40, 0x40000
	global_load_lds_dwordx4 v128, s[40:41]
	s_addc_u32 s19, s41, 0
	s_add_i32 m0, s8, 0x14000
	v_mov_b32_e32 v134, v242
	global_load_lds_dwordx4 v132, s[18:19]
	s_add_i32 m0, s8, 0x16000
	s_add_u32 s38, s10, s14
	s_addc_u32 s39, s11, s15
	s_add_i32 s9, s8, 0x2000
	global_load_lds_dwordx4 v128, s[18:19]
	s_mov_b32 m0, s8
	s_add_u32 s14, s38, 0x40000
	global_load_lds_dwordx4 v134, s[38:39]
	s_mov_b32 m0, s9
	s_addc_u32 s15, s39, 0
	s_add_i32 s34, s8, 0x4000
	global_load_lds_dwordx4 v130, s[38:39]
	s_mov_b32 m0, s34
	s_add_i32 s35, s8, 0x6000
	global_load_lds_dwordx4 v134, s[14:15]
	s_mov_b32 m0, s35
	v_mov_b32_e32 v133, 0
	global_load_lds_dwordx4 v130, s[14:15]
	v_mov_b32_e32 v129, v133
	v_mov_b32_e32 v135, v133
	v_mov_b32_e32 v131, v133
	s_cmp_eq_u32 s16, 1
	s_mov_b64 s[64:65], s[48:49]
	s_mov_b32 s37, 0
	v_lshl_add_u64 v[6:7], s[40:41], 0, v[132:133]
	v_lshl_add_u64 v[4:5], s[40:41], 0, v[128:129]
	v_lshl_add_u64 v[0:1], s[38:39], 0, v[134:135]
	s_cselect_b64 s[14:15], -1, 0
	s_cmp_lg_u32 s16, 1
	v_lshl_add_u64 v[2:3], s[38:39], 0, v[130:131]
	s_cbranch_scc1 .LBB0_765
	s_barrier

; #define PG8_STAGE(bufoff, gbase, voff) do { _Pragma("unroll") for (int _i = 0; _i < 2; ++_i) \
;         __builtin_amdgcn_global_load_lds((const unsigned*)((const char*)(gbase) + (voff)[_i]), (PG8_LAS unsigned*)(lds + (bufoff) + ldsw + _i * 8192), 16, 0, 0); } while (0)
; #define PG8_LDA(dst, b, h) do { _Pragma("unroll") for (int m = 0; m < 4; ++m) _Pragma("unroll") for (int k = 0; k < 2; ++k) dst[m][k] = *(const PG8_LAS bf16x8*)(lds + PG8_SA(b, h) + aoff + m * 2048 + k * 1024); } while (0)
; #define PG8_LDB(dst, b, h) do { _Pragma("unroll") for (int n = 0; n < 2; ++n) _Pragma("unroll") for (int k = 0; k < 2; ++k) dst[n][k] = *(const PG8_LAS bf16x8*)(lds + PG8_SB(b, h) + boff + n * 2048 + k * 1024); } while (0)
; #define PG8_WAIT_V(n) asm volatile("s_waitcnt vmcnt(" #n ")" ::: "memory")
; #define PG8_WAIT_L(n) asm volatile("s_waitcnt lgkmcnt(" #n ")" ::: "memory")
; template <class Epi, class Sched, bool ALIGN_EPI = false, bool SP2 = false>
; __device__ __forceinline__ void gemm_phase(PG8_LAS unsigned char* lds, const Gemm g, const Sched& S, const Epi& E) {
;     ...
;         const char* nA = has_next ? (const char*)(nxt.seg ? g.A1 : g.A0) + (size_t)nxt.pm * tstep : cA; const char* nB = has_next ? (const char*)(nxt.seg ? g.B1 : g.B0) + (size_t)nxt.pn * tstep : cB;
;         for (int t = 0; t < nt; t += 2) {
;             const bool last = (t == nt - 2);
;             const char* a1 = cA + (size_t)(t + 1) * kstep;
;             const char* a2 = last ? nA : cA + (size_t)(t + 2) * kstep; const char* b2 = last ? nB : cB + (size_t)(t + 2) * kstep;
;             const char* a3 = a2 + kstep; const char* b3 = b2 + kstep;
;             if (last && has_next) S.a_ready(nxt);
;             if constexpr (SP2) {
;             PG8_LDB(B0, 0, 0); PG8_LDB(B1, 0, 1); PG8_SCHED; PG8_LDA(At, 0, 0); PG8_STAGE(PG8_SA(1, 1), a1 + hstep, voffA);
;             PG8_WAIT_V(8); PG8_WAIT_L(0); PG8_BAR; PG8_MMA(0, 0, At, B0); PG8_MMA(0, 1, At, B1); PG8_BAR; PG8_SCHED;
;     ...
;         if (!(Epi::KEEP && cur.seg == 0)) {
; #pragma unroll
;         for (int a = 0; a < 2; ++a)
; #pragma unroll
;             for (int b = 0; b < 2; ++b)
; #pragma unroll
;                 for (int m = 0; m < 4; ++m)
; #pragma unroll
;                     for (int n = 0; n < 2; ++n) acc[a][b][m][n] = (f32x4){0.f, 0.f, 0.f, 0.f};
;         }
;         cur = nxt; cA = nA; cB = nB; ++ui;
.LBB0_770:
	s_ashr_i32 s21, s20, 31
	s_lshl_b64 s[24:25], s[20:21], 19
	s_add_u32 s24, s10, s24
	s_addc_u32 s25, s11, s25
	s_and_b64 s[26:27], s[4:5], exec
	s_cselect_b32 s21, s25, s39
	s_cselect_b32 s53, s24, s38
	s_ashr_i32 s23, s22, 31
	s_lshl_b64 s[26:27], s[22:23], 19
	s_add_u32 s26, s60, s26
	s_addc_u32 s27, s61, s27
	s_and_b64 s[30:31], s[4:5], exec
	s_cselect_b32 s23, s27, s41
	s_cselect_b32 s54, s26, s40
	s_add_u32 s38, s38, 0x40080
	s_addc_u32 s39, s39, 0
	s_add_u32 s55, s40, 0x100
	v_mov_b32_e32 v0, 0
	s_addc_u32 s3, s41, 0
	s_mov_b32 s30, -2
	v_mov_b32_e32 v1, v0
	v_mov_b32_e32 v2, v0
	v_mov_b32_e32 v3, v0
	v_mov_b32_e32 v4, v0
	v_mov_b32_e32 v5, v0
	v_mov_b32_e32 v6, v0
	v_mov_b32_e32 v7, v0
	v_mov_b32_e32 v16, v0
	v_mov_b32_e32 v17, v0
	v_mov_b32_e32 v18, v0
	v_mov_b32_e32 v19, v0
	v_mov_b32_e32 v20, v0
	v_mov_b32_e32 v21, v0
	v_mov_b32_e32 v22, v0
	v_mov_b32_e32 v23, v0
	v_mov_b32_e32 v32, v0
	v_mov_b32_e32 v33, v0
	v_mov_b32_e32 v34, v0
	v_mov_b32_e32 v35, v0
	v_mov_b32_e32 v36, v0
	v_mov_b32_e32 v37, v0
	v_mov_b32_e32 v38, v0
	v_mov_b32_e32 v39, v0
	v_mov_b32_e32 v48, v0
	v_mov_b32_e32 v49, v0
	v_mov_b32_e32 v50, v0
	v_mov_b32_e32 v51, v0
	v_mov_b32_e32 v52, v0
	v_mov_b32_e32 v53, v0
	v_mov_b32_e32 v54, v0
	v_mov_b32_e32 v55, v0
	v_mov_b32_e32 v8, v0
	v_mov_b32_e32 v9, v0
	v_mov_b32_e32 v10, v0
	v_mov_b32_e32 v11, v0
	v_mov_b32_e32 v12, v0
	v_mov_b32_e32 v13, v0
	v_mov_b32_e32 v14, v0
	v_mov_b32_e32 v15, v0
	v_mov_b32_e32 v24, v0
	v_mov_b32_e32 v25, v0
	v_mov_b32_e32 v26, v0
	v_mov_b32_e32 v27, v0
	v_mov_b32_e32 v28, v0
	v_mov_b32_e32 v29, v0
	v_mov_b32_e32 v30, v0
	v_mov_b32_e32 v31, v0
	v_mov_b32_e32 v40, v0
	v_mov_b32_e32 v41, v0
	v_mov_b32_e32 v42, v0
	v_mov_b32_e32 v43, v0
	v_mov_b32_e32 v44, v0
	v_mov_b32_e32 v45, v0
	v_mov_b32_e32 v46, v0
	v_mov_b32_e32 v47, v0
	v_mov_b32_e32 v56, v0
	v_mov_b32_e32 v57, v0
	v_mov_b32_e32 v58, v0
	v_mov_b32_e32 v59, v0
	v_mov_b32_e32 v60, v0
	v_mov_b32_e32 v61, v0
	v_mov_b32_e32 v62, v0
	v_mov_b32_e32 v63, v0
	v_mov_b32_e32 v64, v0
	v_mov_b32_e32 v65, v0
	v_mov_b32_e32 v66, v0
	v_mov_b32_e32 v67, v0
	v_mov_b32_e32 v68, v0
	v_mov_b32_e32 v69, v0
	v_mov_b32_e32 v70, v0
	v_mov_b32_e32 v71, v0
	v_mov_b32_e32 v80, v0
	v_mov_b32_e32 v81, v0
	v_mov_b32_e32 v82, v0
	v_mov_b32_e32 v83, v0
	v_mov_b32_e32 v84, v0
	v_mov_b32_e32 v85, v0
	v_mov_b32_e32 v86, v0
	v_mov_b32_e32 v87, v0
	v_mov_b32_e32 v96, v0
	v_mov_b32_e32 v97, v0
	v_mov_b32_e32 v98, v0
	v_mov_b32_e32 v99, v0
	v_mov_b32_e32 v100, v0
	v_mov_b32_e32 v101, v0
	v_mov_b32_e32 v102, v0
	v_mov_b32_e32 v103, v0
	v_mov_b32_e32 v108, v0
	v_mov_b32_e32 v109, v0
	v_mov_b32_e32 v110, v0
	v_mov_b32_e32 v111, v0
	v_mov_b32_e32 v112, v0
	v_mov_b32_e32 v113, v0
	v_mov_b32_e32 v114, v0
	v_mov_b32_e32 v115, v0
	v_mov_b32_e32 v72, v0
	v_mov_b32_e32 v73, v0
	v_mov_b32_e32 v74, v0
	v_mov_b32_e32 v75, v0
	v_mov_b32_e32 v76, v0
	v_mov_b32_e32 v77, v0
	v_mov_b32_e32 v78, v0
	v_mov_b32_e32 v79, v0
	v_mov_b32_e32 v88, v0
	v_mov_b32_e32 v89, v0
	v_mov_b32_e32 v90, v0
	v_mov_b32_e32 v91, v0
	v_mov_b32_e32 v92, v0
	v_mov_b32_e32 v93, v0
	v_mov_b32_e32 v94, v0
	v_mov_b32_e32 v95, v0
	v_mov_b32_e32 v104, v0
	v_mov_b32_e32 v105, v0
	v_mov_b32_e32 v106, v0
	v_mov_b32_e32 v107, v0
	v_mov_b32_e32 v116, v0
	v_mov_b32_e32 v117, v0
	v_mov_b32_e32 v118, v0
	v_mov_b32_e32 v119, v0
	v_mov_b32_e32 v120, v0
	v_mov_b32_e32 v121, v0
	v_mov_b32_e32 v122, v0
	v_mov_b32_e32 v123, v0
	v_mov_b32_e32 v124, v0
	v_mov_b32_e32 v125, v0
	v_mov_b32_e32 v126, v0
	v_mov_b32_e32 v127, v0
	s_cmp_eq_u32 s66, 0
	s_cbranch_scc1 .LBB0_771
	ds_read_b128 v[144:147], v151
	ds_read_b128 v[156:159], v249
	ds_read_b128 v[160:163], v151 offset:2048
	ds_read_b128 v[166:169], v249 offset:2048
	ds_read_b128 v[170:173], v152
	ds_read_b128 v[174:177], v250
	ds_read_b128 v[178:181], v152 offset:2048
	ds_read_b128 v[182:185], v250 offset:2048
	s_add_u32 s31, s38, 0xfffc0080
	s_addc_u32 s40, s39, -1
	s_cmp_eq_u32 s30, 12
	s_cselect_b32 s43, s21, s40
	s_cselect_b32 s42, s53, s31
	s_cselect_b32 s41, s23, s3
	s_cselect_b32 s40, s54, s55
	s_add_i32 m0, s8, 0xc000
	ds_read_b128 v[186:189], v153
	ds_read_b128 v[190:193], v251
	ds_read_b128 v[194:197], v153 offset:2048
	ds_read_b128 v[198:201], v251 offset:2048
	ds_read_b128 v[202:205], v153 offset:4096
	ds_read_b128 v[206:209], v251 offset:4096
	ds_read_b128 v[210:213], v153 offset:6144
	ds_read_b128 v[214:217], v251 offset:6144
	global_load_lds_dwordx4 v136, s[38:39]
	s_add_i32 m0, s8, 0xe000
	s_nop 0
	global_load_lds_dwordx4 v138, s[38:39]
	s_waitcnt vmcnt(10)
	s_waitcnt lgkmcnt(0)
	s_barrier
; #define PG8_STAGE(bufoff, gbase, voff) do { _Pragma("unroll") for (int _i = 0; _i < 2; ++_i) \
;         __builtin_amdgcn_global_load_lds((const unsigned*)((const char*)(gbase) + (voff)[_i]), (PG8_LAS unsigned*)(lds + (bufoff) + ldsw + _i * 8192), 16, 0, 0); } while (0)
; #define PG8_LDA(dst, b, h) do { _Pragma("unroll") for (int m = 0; m < 4; ++m) _Pragma("unroll") for (int k = 0; k < 2; ++k) dst[m][k] = *(const PG8_LAS bf16x8*)(lds + PG8_SA(b, h) + aoff + m * 2048 + k * 1024); } while (0)
; #define PG8_LDB(dst, b, h) do { _Pragma("unroll") for (int n = 0; n < 2; ++n) _Pragma("unroll") for (int k = 0; k < 2; ++k) dst[n][k] = *(const PG8_LAS bf16x8*)(lds + PG8_SB(b, h) + boff + n * 2048 + k * 1024); } while (0)
; #define PG8_MMA(ai, bj, At, Bt) do { __builtin_amdgcn_s_setprio(1); _Pragma("unroll") for (int m = 0; m < 4; ++m) _Pragma("unroll") for (int n = 0; n < 2; ++n) _Pragma("unroll") for (int k = 0; k < 2; ++k) \
;         acc[ai][bj][m][n] = __builtin_amdgcn_mfma_f32_16x16x32_bf16(Bt[n][k], At[m][k], acc[ai][bj][m][n], 0, 0, 0); __builtin_amdgcn_s_setprio(0); } while (0)
; #define PG8_WAIT_V(n) asm volatile("s_waitcnt vmcnt(" #n ")" ::: "memory")
; #define PG8_WAIT_L(n) asm volatile("s_waitcnt lgkmcnt(" #n ")" ::: "memory")
; #define PG8_BAR __builtin_amdgcn_s_barrier()
; #define PG8_SCHED __builtin_amdgcn_sched_barrier(0)
; template <class Epi, class Sched, bool ALIGN_EPI = false, bool SP2 = false>
; __device__ __forceinline__ void gemm_phase(PG8_LAS unsigned char* lds, const Gemm g, const Sched& S, const Epi& E) {
;     ...
;             PG8_LDB(B0, 0, 0); PG8_LDB(B1, 0, 1); PG8_SCHED; PG8_LDA(At, 0, 0); PG8_STAGE(PG8_SA(1, 1), a1 + hstep, voffA);
;             PG8_WAIT_V(8); PG8_WAIT_L(0); PG8_BAR; PG8_MMA(0, 0, At, B0); PG8_MMA(0, 1, At, B1); PG8_BAR; PG8_SCHED;
;             PG8_LDA(At, 0, 1); PG8_STAGE(PG8_SB(0, 0), b2, voffB); PG8_STAGE(PG8_SB(0, 1), b2 + hstep, voffB); PG8_STAGE(PG8_SA(0, 0), a2, voffA);
;             PG8_WAIT_V(8); PG8_WAIT_L(0); PG8_BAR; PG8_MMA(1, 0, At, B0); PG8_MMA(1, 1, At, B1); PG8_BAR; PG8_SCHED;
	s_setprio 1
	s_waitcnt lgkmcnt(0)
	v_mfma_f32_16x16x32_bf16 v[124:127], v[144:147], v[186:189], v[124:127]
	v_mfma_f32_16x16x32_bf16 v[120:123], v[160:163], v[186:189], v[120:123]
	v_mfma_f32_16x16x32_bf16 v[116:119], v[144:147], v[194:197], v[116:119]
	v_mfma_f32_16x16x32_bf16 v[104:107], v[160:163], v[194:197], v[104:107]
	v_mfma_f32_16x16x32_bf16 v[92:95], v[144:147], v[202:205], v[92:95]
	v_mfma_f32_16x16x32_bf16 v[88:91], v[160:163], v[202:205], v[88:91]
	v_mfma_f32_16x16x32_bf16 v[76:79], v[144:147], v[210:213], v[76:79]
	v_mfma_f32_16x16x32_bf16 v[72:75], v[160:163], v[210:213], v[72:75]
	v_mfma_f32_16x16x32_bf16 v[124:127], v[156:159], v[190:193], v[124:127]
	v_mfma_f32_16x16x32_bf16 v[120:123], v[166:169], v[190:193], v[120:123]
	v_mfma_f32_16x16x32_bf16 v[116:119], v[156:159], v[198:201], v[116:119]
	v_mfma_f32_16x16x32_bf16 v[104:107], v[166:169], v[198:201], v[104:107]
	v_mfma_f32_16x16x32_bf16 v[92:95], v[156:159], v[206:209], v[92:95]
	v_mfma_f32_16x16x32_bf16 v[88:91], v[166:169], v[206:209], v[88:91]
	v_mfma_f32_16x16x32_bf16 v[76:79], v[156:159], v[214:217], v[76:79]
	v_mfma_f32_16x16x32_bf16 v[72:75], v[166:169], v[214:217], v[72:75]
	s_setprio 0
	s_setprio 1
	v_mfma_f32_16x16x32_bf16 v[112:115], v[170:173], v[186:189], v[112:115]
	v_mfma_f32_16x16x32_bf16 v[108:111], v[178:181], v[186:189], v[108:111]
	v_mfma_f32_16x16x32_bf16 v[100:103], v[170:173], v[194:197], v[100:103]
	v_mfma_f32_16x16x32_bf16 v[96:99], v[178:181], v[194:197], v[96:99]
	v_mfma_f32_16x16x32_bf16 v[84:87], v[170:173], v[202:205], v[84:87]
	v_mfma_f32_16x16x32_bf16 v[80:83], v[178:181], v[202:205], v[80:83]
	v_mfma_f32_16x16x32_bf16 v[68:71], v[170:173], v[210:213], v[68:71]
	v_mfma_f32_16x16x32_bf16 v[64:67], v[178:181], v[210:213], v[64:67]
	v_mfma_f32_16x16x32_bf16 v[112:115], v[174:177], v[190:193], v[112:115]
	v_mfma_f32_16x16x32_bf16 v[108:111], v[182:185], v[190:193], v[108:111]
	v_mfma_f32_16x16x32_bf16 v[100:103], v[174:177], v[198:201], v[100:103]
	v_mfma_f32_16x16x32_bf16 v[96:99], v[182:185], v[198:201], v[96:99]
	v_mfma_f32_16x16x32_bf16 v[84:87], v[174:177], v[206:209], v[84:87]
	v_mfma_f32_16x16x32_bf16 v[80:83], v[182:185], v[206:209], v[80:83]
	v_mfma_f32_16x16x32_bf16 v[68:71], v[174:177], v[214:217], v[68:71]
	v_mfma_f32_16x16x32_bf16 v[64:67], v[182:185], v[214:217], v[64:67]
	s_setprio 0
	s_barrier
	s_add_i32 s31, s49, s6
	s_mov_b32 m0, s31
	ds_read_b128 v[186:189], v153 offset:16384
	ds_read_b128 v[190:193], v251 offset:16384
	ds_read_b128 v[194:197], v153 offset:18432
	ds_read_b128 v[198:201], v251 offset:18432
	ds_read_b128 v[202:205], v153 offset:20480
	ds_read_b128 v[206:209], v251 offset:20480
	ds_read_b128 v[210:213], v153 offset:22528
	ds_read_b128 v[214:217], v251 offset:22528
	global_load_lds_dwordx4 v132, s[40:41]
	s_add_i32 m0, s31, 0x2000
	s_add_u32 s58, s40, 0x40000
	s_addc_u32 s59, s41, 0
	s_add_i32 s31, s50, s6
	global_load_lds_dwordx4 v128, s[40:41]
	s_mov_b32 m0, s31
	s_nop 0
	global_load_lds_dwordx4 v132, s[58:59]
	s_add_i32 m0, s31, 0x2000
	s_nop 0
	global_load_lds_dwordx4 v128, s[58:59]
	s_mov_b32 m0, s8
	s_nop 0
	global_load_lds_dwordx4 v134, s[42:43]
	s_mov_b32 m0, s9
	s_nop 0
	global_load_lds_dwordx4 v130, s[42:43]
	s_waitcnt vmcnt(16)
	s_waitcnt lgkmcnt(0)
	s_barrier
	s_setprio 1
	s_waitcnt lgkmcnt(0)
	v_mfma_f32_16x16x32_bf16 v[60:63], v[144:147], v[186:189], v[60:63]
	v_mfma_f32_16x16x32_bf16 v[56:59], v[160:163], v[186:189], v[56:59]
	v_mfma_f32_16x16x32_bf16 v[44:47], v[144:147], v[194:197], v[44:47]
	v_mfma_f32_16x16x32_bf16 v[40:43], v[160:163], v[194:197], v[40:43]
	v_mfma_f32_16x16x32_bf16 v[28:31], v[144:147], v[202:205], v[28:31]
	v_mfma_f32_16x16x32_bf16 v[24:27], v[160:163], v[202:205], v[24:27]
	v_mfma_f32_16x16x32_bf16 v[12:15], v[144:147], v[210:213], v[12:15]
	v_mfma_f32_16x16x32_bf16 v[8:11], v[160:163], v[210:213], v[8:11]
	v_mfma_f32_16x16x32_bf16 v[60:63], v[156:159], v[190:193], v[60:63]
	v_mfma_f32_16x16x32_bf16 v[56:59], v[166:169], v[190:193], v[56:59]
	v_mfma_f32_16x16x32_bf16 v[44:47], v[156:159], v[198:201], v[44:47]
	v_mfma_f32_16x16x32_bf16 v[40:43], v[166:169], v[198:201], v[40:43]
	v_mfma_f32_16x16x32_bf16 v[28:31], v[156:159], v[206:209], v[28:31]
	v_mfma_f32_16x16x32_bf16 v[24:27], v[166:169], v[206:209], v[24:27]
	v_mfma_f32_16x16x32_bf16 v[12:15], v[156:159], v[214:217], v[12:15]
	v_mfma_f32_16x16x32_bf16 v[8:11], v[166:169], v[214:217], v[8:11]
	s_setprio 0
	s_setprio 1
	v_mfma_f32_16x16x32_bf16 v[52:55], v[170:173], v[186:189], v[52:55]
	v_mfma_f32_16x16x32_bf16 v[48:51], v[178:181], v[186:189], v[48:51]
	v_mfma_f32_16x16x32_bf16 v[36:39], v[170:173], v[194:197], v[36:39]
	v_mfma_f32_16x16x32_bf16 v[32:35], v[178:181], v[194:197], v[32:35]
	v_mfma_f32_16x16x32_bf16 v[20:23], v[170:173], v[202:205], v[20:23]
	v_mfma_f32_16x16x32_bf16 v[16:19], v[178:181], v[202:205], v[16:19]
	v_mfma_f32_16x16x32_bf16 v[4:7], v[170:173], v[210:213], v[4:7]
	v_mfma_f32_16x16x32_bf16 v[0:3], v[178:181], v[210:213], v[0:3]
	v_mfma_f32_16x16x32_bf16 v[52:55], v[174:177], v[190:193], v[52:55]
	v_mfma_f32_16x16x32_bf16 v[48:51], v[182:185], v[190:193], v[48:51]
	v_mfma_f32_16x16x32_bf16 v[36:39], v[174:177], v[198:201], v[36:39]
	v_mfma_f32_16x16x32_bf16 v[32:35], v[182:185], v[198:201], v[32:35]
	v_mfma_f32_16x16x32_bf16 v[20:23], v[174:177], v[206:209], v[20:23]
	v_mfma_f32_16x16x32_bf16 v[16:19], v[182:185], v[206:209], v[16:19]
	v_mfma_f32_16x16x32_bf16 v[4:7], v[174:177], v[214:217], v[4:7]
	v_mfma_f32_16x16x32_bf16 v[0:3], v[182:185], v[214:217], v[0:3]
	s_setprio 0
	s_barrier
; #define PG8_STAGE(bufoff, gbase, voff) do { _Pragma("unroll") for (int _i = 0; _i < 2; ++_i) \
;         __builtin_amdgcn_global_load_lds((const unsigned*)((const char*)(gbase) + (voff)[_i]), (PG8_LAS unsigned*)(lds + (bufoff) + ldsw + _i * 8192), 16, 0, 0); } while (0)
; #define PG8_LDA(dst, b, h) do { _Pragma("unroll") for (int m = 0; m < 4; ++m) _Pragma("unroll") for (int k = 0; k < 2; ++k) dst[m][k] = *(const PG8_LAS bf16x8*)(lds + PG8_SA(b, h) + aoff + m * 2048 + k * 1024); } while (0)
; #define PG8_LDB(dst, b, h) do { _Pragma("unroll") for (int n = 0; n < 2; ++n) _Pragma("unroll") for (int k = 0; k < 2; ++k) dst[n][k] = *(const PG8_LAS bf16x8*)(lds + PG8_SB(b, h) + boff + n * 2048 + k * 1024); } while (0)
; template <class Epi, class Sched, bool ALIGN_EPI = false, bool SP2 = false>
; __device__ __forceinline__ void gemm_phase(PG8_LAS unsigned char* lds, const Gemm g, const Sched& S, const Epi& E) {
;     ...
;         for (int t = 0; t < nt; t += 2) {
;             const bool last = (t == nt - 2);
;             const char* a1 = cA + (size_t)(t + 1) * kstep;
;             const char* a2 = last ? nA : cA + (size_t)(t + 2) * kstep; const char* b2 = last ? nB : cB + (size_t)(t + 2) * kstep;
;             const char* a3 = a2 + kstep; const char* b3 = b2 + kstep;
;             if (last && has_next) S.a_ready(nxt);
;             if constexpr (SP2) {
;             PG8_LDB(B0, 0, 0); PG8_LDB(B1, 0, 1); PG8_SCHED; PG8_LDA(At, 0, 0); PG8_STAGE(PG8_SA(1, 1), a1 + hstep, voffA);
;             PG8_WAIT_V(8); PG8_WAIT_L(0); PG8_BAR; PG8_MMA(0, 0, At, B0); PG8_MMA(0, 1, At, B1); PG8_BAR; PG8_SCHED;
;             PG8_LDA(At, 0, 1); PG8_STAGE(PG8_SB(0, 0), b2, voffB); PG8_STAGE(PG8_SB(0, 1), b2 + hstep, voffB); PG8_STAGE(PG8_SA(0, 0), a2, voffA);
;             PG8_WAIT_V(8); PG8_WAIT_L(0); PG8_BAR; PG8_MMA(1, 0, At, B0); PG8_MMA(1, 1, At, B1); PG8_BAR; PG8_SCHED;
;             PG8_LDB(B0, 1, 0); PG8_LDB(B1, 1, 1); PG8_SCHED; PG8_LDA(At, 1, 0); PG8_STAGE(PG8_SA(0, 1), a2 + hstep, voffA);
;             PG8_WAIT_V(8); PG8_WAIT_L(0); PG8_BAR; PG8_MMA(0, 0, At, B0); PG8_MMA(0, 1, At, B1); PG8_BAR; PG8_SCHED;
;             PG8_LDA(At, 1, 1); PG8_STAGE(PG8_SB(1, 0), b3, voffB); PG8_STAGE(PG8_SB(1, 1), b3 + hstep, voffB); PG8_STAGE(PG8_SA(1, 0), a3, voffA);
;             PG8_WAIT_V(8); PG8_WAIT_L(0); PG8_BAR; PG8_MMA(1, 0, At, B0); PG8_MMA(1, 1, At, B1); PG8_BAR; PG8_SCHED;
	s_add_i32 s31, 0, 0x18000
	v_add_u32_e32 v165, s31, v149
	v_xor_b32_e32 v252, 64, v165
	s_add_i32 s58, 0, 0x1c000
	ds_read_b128 v[144:147], v165
	ds_read_b128 v[156:159], v252
	ds_read_b128 v[160:163], v165 offset:2048
	ds_read_b128 v[166:169], v252 offset:2048
	v_add_u32_e32 v165, s58, v149
	v_xor_b32_e32 v252, 64, v165
	ds_read_b128 v[170:173], v165
	ds_read_b128 v[174:177], v252
	ds_read_b128 v[178:181], v165 offset:2048
	ds_read_b128 v[182:185], v252 offset:2048
	s_add_u32 s42, s42, 0x40000
	s_addc_u32 s43, s43, 0
	s_mov_b32 m0, s34
	ds_read_b128 v[186:189], v153 offset:32768
	ds_read_b128 v[190:193], v251 offset:32768
	ds_read_b128 v[194:197], v153 offset:34816
	ds_read_b128 v[198:201], v251 offset:34816
	ds_read_b128 v[202:205], v153 offset:36864
	ds_read_b128 v[206:209], v251 offset:36864
	ds_read_b128 v[210:213], v153 offset:38912
	ds_read_b128 v[214:217], v251 offset:38912
	global_load_lds_dwordx4 v134, s[42:43]
	s_mov_b32 m0, s35
	s_nop 0
	global_load_lds_dwordx4 v130, s[42:43]
	s_waitcnt vmcnt(8)
	s_waitcnt lgkmcnt(0)
	s_barrier
	s_setprio 1
	s_waitcnt lgkmcnt(0)
	v_mfma_f32_16x16x32_bf16 v[124:127], v[144:147], v[186:189], v[124:127]
	v_mfma_f32_16x16x32_bf16 v[120:123], v[160:163], v[186:189], v[120:123]
	v_mfma_f32_16x16x32_bf16 v[116:119], v[144:147], v[194:197], v[116:119]
	v_mfma_f32_16x16x32_bf16 v[104:107], v[160:163], v[194:197], v[104:107]
	v_mfma_f32_16x16x32_bf16 v[92:95], v[144:147], v[202:205], v[92:95]
	v_mfma_f32_16x16x32_bf16 v[88:91], v[160:163], v[202:205], v[88:91]
	v_mfma_f32_16x16x32_bf16 v[76:79], v[144:147], v[210:213], v[76:79]
	v_mfma_f32_16x16x32_bf16 v[72:75], v[160:163], v[210:213], v[72:75]
	v_mfma_f32_16x16x32_bf16 v[124:127], v[156:159], v[190:193], v[124:127]
	v_mfma_f32_16x16x32_bf16 v[120:123], v[166:169], v[190:193], v[120:123]
	v_mfma_f32_16x16x32_bf16 v[116:119], v[156:159], v[198:201], v[116:119]
	v_mfma_f32_16x16x32_bf16 v[104:107], v[166:169], v[198:201], v[104:107]
	v_mfma_f32_16x16x32_bf16 v[92:95], v[156:159], v[206:209], v[92:95]
	v_mfma_f32_16x16x32_bf16 v[88:91], v[166:169], v[206:209], v[88:91]
	v_mfma_f32_16x16x32_bf16 v[76:79], v[156:159], v[214:217], v[76:79]
	v_mfma_f32_16x16x32_bf16 v[72:75], v[166:169], v[214:217], v[72:75]
	s_setprio 0
	s_setprio 1
	v_mfma_f32_16x16x32_bf16 v[112:115], v[170:173], v[186:189], v[112:115]
	v_mfma_f32_16x16x32_bf16 v[108:111], v[178:181], v[186:189], v[108:111]
	v_mfma_f32_16x16x32_bf16 v[100:103], v[170:173], v[194:197], v[100:103]
	v_mfma_f32_16x16x32_bf16 v[96:99], v[178:181], v[194:197], v[96:99]
	v_mfma_f32_16x16x32_bf16 v[84:87], v[170:173], v[202:205], v[84:87]
	v_mfma_f32_16x16x32_bf16 v[80:83], v[178:181], v[202:205], v[80:83]
	v_mfma_f32_16x16x32_bf16 v[68:71], v[170:173], v[210:213], v[68:71]
	v_mfma_f32_16x16x32_bf16 v[64:67], v[178:181], v[210:213], v[64:67]
	v_mfma_f32_16x16x32_bf16 v[112:115], v[174:177], v[190:193], v[112:115]
	v_mfma_f32_16x16x32_bf16 v[108:111], v[182:185], v[190:193], v[108:111]
	v_mfma_f32_16x16x32_bf16 v[100:103], v[174:177], v[198:201], v[100:103]
	v_mfma_f32_16x16x32_bf16 v[96:99], v[182:185], v[198:201], v[96:99]
	v_mfma_f32_16x16x32_bf16 v[84:87], v[174:177], v[206:209], v[84:87]
	v_mfma_f32_16x16x32_bf16 v[80:83], v[182:185], v[206:209], v[80:83]
	v_mfma_f32_16x16x32_bf16 v[68:71], v[174:177], v[214:217], v[68:71]
	v_mfma_f32_16x16x32_bf16 v[64:67], v[182:185], v[214:217], v[64:67]
	s_setprio 0
	s_barrier
	s_add_i32 s31, s31, s6
	s_add_i32 m0, s31, 0xffffff80
	ds_read_b128 v[186:189], v153 offset:49152
	ds_read_b128 v[190:193], v251 offset:49152
	ds_read_b128 v[194:197], v153 offset:51200
	ds_read_b128 v[198:201], v251 offset:51200
	ds_read_b128 v[202:205], v153 offset:53248
	ds_read_b128 v[206:209], v251 offset:53248
	ds_read_b128 v[210:213], v153 offset:55296
	ds_read_b128 v[214:217], v251 offset:55296
	global_load_lds_dwordx4 v132, s[40:41] offset:128
	s_add_i32 m0, s31, 0x1f80
	s_add_i32 s31, s58, s6
	global_load_lds_dwordx4 v128, s[40:41] offset:128
	s_add_u32 s40, s40, 0x40080
	s_addc_u32 s41, s41, 0
	s_mov_b32 m0, s31
	s_nop 0
	global_load_lds_dwordx4 v132, s[40:41]
	s_add_i32 m0, s31, 0x2000
	s_nop 0
	global_load_lds_dwordx4 v128, s[40:41]
	s_sub_u32 s98, s42, 0x3ff80
	s_subb_u32 s99, s43, 0
	s_mov_b32 m0, s46
	s_nop 0
	global_load_lds_dwordx4 v134, s[98:99]
	s_mov_b32 m0, s47
	s_nop 0
	global_load_lds_dwordx4 v130, s[98:99]
	s_waitcnt vmcnt(8)
	s_waitcnt lgkmcnt(0)
	s_barrier
	s_setprio 1
	s_waitcnt lgkmcnt(0)
	v_mfma_f32_16x16x32_bf16 v[60:63], v[144:147], v[186:189], v[60:63]
	v_mfma_f32_16x16x32_bf16 v[56:59], v[160:163], v[186:189], v[56:59]
	v_mfma_f32_16x16x32_bf16 v[44:47], v[144:147], v[194:197], v[44:47]
	v_mfma_f32_16x16x32_bf16 v[40:43], v[160:163], v[194:197], v[40:43]
	v_mfma_f32_16x16x32_bf16 v[28:31], v[144:147], v[202:205], v[28:31]
	v_mfma_f32_16x16x32_bf16 v[24:27], v[160:163], v[202:205], v[24:27]
	v_mfma_f32_16x16x32_bf16 v[12:15], v[144:147], v[210:213], v[12:15]
	v_mfma_f32_16x16x32_bf16 v[8:11], v[160:163], v[210:213], v[8:11]
	v_mfma_f32_16x16x32_bf16 v[60:63], v[156:159], v[190:193], v[60:63]
	v_mfma_f32_16x16x32_bf16 v[56:59], v[166:169], v[190:193], v[56:59]
	v_mfma_f32_16x16x32_bf16 v[44:47], v[156:159], v[198:201], v[44:47]
	v_mfma_f32_16x16x32_bf16 v[40:43], v[166:169], v[198:201], v[40:43]
	v_mfma_f32_16x16x32_bf16 v[28:31], v[156:159], v[206:209], v[28:31]
	v_mfma_f32_16x16x32_bf16 v[24:27], v[166:169], v[206:209], v[24:27]
	v_mfma_f32_16x16x32_bf16 v[12:15], v[156:159], v[214:217], v[12:15]
	v_mfma_f32_16x16x32_bf16 v[8:11], v[166:169], v[214:217], v[8:11]
	s_setprio 0
	s_setprio 1
	v_mfma_f32_16x16x32_bf16 v[52:55], v[170:173], v[186:189], v[52:55]
	v_mfma_f32_16x16x32_bf16 v[48:51], v[178:181], v[186:189], v[48:51]
	v_mfma_f32_16x16x32_bf16 v[36:39], v[170:173], v[194:197], v[36:39]
	v_mfma_f32_16x16x32_bf16 v[32:35], v[178:181], v[194:197], v[32:35]
	v_mfma_f32_16x16x32_bf16 v[20:23], v[170:173], v[202:205], v[20:23]
	v_mfma_f32_16x16x32_bf16 v[16:19], v[178:181], v[202:205], v[16:19]
	v_mfma_f32_16x16x32_bf16 v[4:7], v[170:173], v[210:213], v[4:7]
	v_mfma_f32_16x16x32_bf16 v[0:3], v[178:181], v[210:213], v[0:3]
	v_mfma_f32_16x16x32_bf16 v[52:55], v[174:177], v[190:193], v[52:55]
	v_mfma_f32_16x16x32_bf16 v[48:51], v[182:185], v[190:193], v[48:51]
	v_mfma_f32_16x16x32_bf16 v[36:39], v[174:177], v[198:201], v[36:39]
	v_mfma_f32_16x16x32_bf16 v[32:35], v[182:185], v[198:201], v[32:35]
	v_mfma_f32_16x16x32_bf16 v[20:23], v[174:177], v[206:209], v[20:23]
	v_mfma_f32_16x16x32_bf16 v[16:19], v[182:185], v[206:209], v[16:19]
	v_mfma_f32_16x16x32_bf16 v[4:7], v[174:177], v[214:217], v[4:7]
	v_mfma_f32_16x16x32_bf16 v[0:3], v[182:185], v[214:217], v[0:3]
	s_setprio 0
	s_barrier
	s_add_i32 s30, s30, 2
	s_add_u32 s38, s38, 0x100
	s_addc_u32 s39, s39, 0
	s_add_u32 s55, s55, 0x100
	s_addc_u32 s3, s3, 0
	s_cmp_gt_u32 s30, 13
	s_cbranch_scc0 .LBB0_771
	s_branch .Lp5_exit

; __device__ __forceinline__ void store8(bf16_t* p, f32x4 a, f32x4 b) { u32x4 w; w.x = cvt_pk_bf16(a[0], a[1]); w.y = cvt_pk_bf16(a[2], a[3]); w.z = cvt_pk_bf16(b[0], b[1]); w.w = cvt_pk_bf16(b[2], b[3]); *(u32x4*)p = w; }
; __device__ __forceinline__ f32x4 sigmoid4(f32x4 x) { f32x4 r; r[0] = sigmoidf_(x[0]); r[1] = sigmoidf_(x[1]); r[2] = sigmoidf_(x[2]); r[3] = sigmoidf_(x[3]); return r; }
; #define PG8_BAR __builtin_amdgcn_s_barrier()
;     __device__ __forceinline__ void operator()(const f32x4 (&acc)[2][2][4][2], const Unit& u, int wr, int wc, int fr, int fq) const {
;         const int row0 = u.pm * BM + wr * 64 + fr, col0 = u.pn * 128 + wc * 32 + 8 * fq, lane = 16 * fq + fr;
;         float rsl[2];
; #pragma unroll
;         for (int ai = 0; ai < 2; ++ai) rsl[ai] = __builtin_amdgcn_rsqf(SS[u.pm * BM + ai * HALF + wr * 64 + lane] * (1.0f / 1024.0f) + NORM_EPS);
; #pragma unroll
;         for (int ai = 0; ai < 2; ++ai)
; #pragma unroll
;             for (int m = 0; m < 4; ++m) { const int row = row0 + ai * HALF + m * 16; const float rs = __shfl(rsl[ai], 16 * m + fr);
;                 f32x4 a[2];
; #pragma unroll
;                 for (int n = 0; n < 2; ++n) { const f32x4 g = acc[ai][0][m][n] * rs, up = acc[ai][1][m][n] * rs; a[n] = g * sigmoid4(g) * up; }
;                 store8(ACT + (size_t)row * 2816 + col0, a[0], a[1]); }
; template <class Epi, class Sched, bool ALIGN_EPI = false, bool SP2 = false>
; __device__ __forceinline__ void gemm_phase(PG8_LAS unsigned char* lds, const Gemm g, const Sched& S, const Epi& E) {
;     ...
;         if constexpr (ALIGN_EPI) { if (wr == 0) PG8_BAR; }
;         if constexpr (!Epi::AFTER_DRAIN) { E(acc, cur, wr, wc, fr, fq); S.done(cur); }
.Lp5_exit:
	s_and_b64 vcc, exec, s[18:19]
	s_cbranch_vccz .LBB0_774
	s_barrier
.LBB0_774:
	s_lshl_b32 s3, s36, 8
	s_add_i32 s3, s3, s44
	v_or_b32_e32 v144, s3, v238
	v_ashrrev_i32_e32 v145, 31, v144
	v_lshl_add_u64 v[146:147], v[144:145], 2, s[62:63]
	global_load_dword v157, v[146:147], off
	v_add_u32_e32 v144, 0x80, v144
	v_ashrrev_i32_e32 v145, 31, v144
	v_lshl_add_u64 v[144:145], v[144:145], 2, s[62:63]
	global_load_dword v161, v[144:145], off
	v_lshl_or_b32 v146, s52, 7, v150
	v_mov_b64_e32 v[144:145], s[12:13]
	v_ashrrev_i32_e32 v147, 31, v146
	v_or_b32_e32 v156, s3, v148
	v_lshlrev_b64 v[146:147], 1, v[146:147]
	v_mad_i64_i32 v[158:159], s[30:31], v156, s51, v[144:145]
	v_lshl_add_u64 v[158:159], v[158:159], 0, v[146:147]
	s_andn2_b64 vcc, exec, s[4:5]
	s_mov_b64 s[4:5], -1
	s_waitcnt vmcnt(0)
	v_fmamk_f32 v157, v157, 0x3a800000, v154
	v_rsq_f32_e32 v163, v157
	v_fmamk_f32 v157, v161, 0x3a800000, v154
	ds_bpermute_b32 v160, v155, v163
	ds_bpermute_b32 v162, v155, v163 offset:64
	v_rsq_f32_e32 v157, v157
	s_waitcnt lgkmcnt(1)
	v_pk_mul_f32 v[126:127], v[126:127], v[160:161] op_sel_hi:[1,0]
	v_pk_mul_f32 v[124:125], v[124:125], v[160:161] op_sel_hi:[1,0]
	v_pk_mul_f32 v[122:123], v[122:123], v[160:161] op_sel_hi:[1,0]
	v_pk_mul_f32 v[120:121], v[120:121], v[160:161] op_sel_hi:[1,0]
	v_pk_mul_f32 v[112:113], v[112:113], v[160:161] op_sel_hi:[1,0]
	v_pk_mul_f32 v[114:115], v[114:115], v[160:161] op_sel_hi:[1,0]
	v_pk_mul_f32 v[108:109], v[108:109], v[160:161] op_sel_hi:[1,0]
	v_pk_mul_f32 v[110:111], v[110:111], v[160:161] op_sel_hi:[1,0]
	s_waitcnt lgkmcnt(0)
	v_pk_mul_f32 v[118:119], v[118:119], v[162:163] op_sel_hi:[1,0]
	v_pk_mul_f32 v[116:117], v[116:117], v[162:163] op_sel_hi:[1,0]
	v_mul_f32_e32 v160, 0xbfb8aa3b, v124
	v_mul_f32_e32 v161, 0xbfb8aa3b, v125
	v_mul_f32_e32 v165, 0xbfb8aa3b, v126
	v_mul_f32_e32 v166, 0xbfb8aa3b, v127
	v_mul_f32_e32 v167, 0xbfb8aa3b, v120
	v_mul_f32_e32 v168, 0xbfb8aa3b, v121
	v_mul_f32_e32 v169, 0xbfb8aa3b, v122
	v_mul_f32_e32 v170, 0xbfb8aa3b, v123
	v_pk_mul_f32 v[104:105], v[104:105], v[162:163] op_sel_hi:[1,0]
	v_mul_f32_e32 v171, 0xbfb8aa3b, v116
	v_mul_f32_e32 v172, 0xbfb8aa3b, v117
	v_mul_f32_e32 v173, 0xbfb8aa3b, v118
	v_mul_f32_e32 v174, 0xbfb8aa3b, v119
	v_exp_f32_e32 v160, v160
	v_exp_f32_e32 v161, v161
	v_exp_f32_e32 v165, v165
	v_exp_f32_e32 v166, v166
	v_exp_f32_e32 v167, v167
	v_exp_f32_e32 v168, v168
	v_exp_f32_e32 v169, v169
	v_exp_f32_e32 v170, v170
	v_mul_f32_e32 v175, 0xbfb8aa3b, v104
	v_exp_f32_e32 v171, v171
	v_exp_f32_e32 v172, v172
	v_exp_f32_e32 v173, v173
	v_exp_f32_e32 v174, v174
	v_exp_f32_e32 v175, v175
	v_add_f32_e32 v160, 1.0, v160
	v_add_f32_e32 v161, 1.0, v161
	v_add_f32_e32 v165, 1.0, v165
	v_add_f32_e32 v177, 1.0, v166
	v_add_f32_e32 v178, 1.0, v167
	v_add_f32_e32 v179, 1.0, v168
	v_add_f32_e32 v180, 1.0, v169
	v_add_f32_e32 v181, 1.0, v170
	v_add_f32_e32 v182, 1.0, v171
	v_add_f32_e32 v183, 1.0, v172
	v_add_f32_e32 v184, 1.0, v173
	v_add_f32_e32 v185, 1.0, v174
	v_rcp_f32_e32 v160, v160
	v_rcp_f32_e32 v161, v161
	v_rcp_f32_e32 v166, v165
	v_rcp_f32_e32 v167, v177
	v_rcp_f32_e32 v168, v178
	v_rcp_f32_e32 v169, v179
	v_rcp_f32_e32 v170, v180
	v_rcp_f32_e32 v171, v181
	v_add_f32_e32 v186, 1.0, v175
	v_rcp_f32_e32 v172, v182
	v_rcp_f32_e32 v173, v183
	v_rcp_f32_e32 v174, v184
	v_rcp_f32_e32 v175, v185
	v_pk_mul_f32 v[124:125], v[124:125], v[160:161]
	v_pk_mul_f32 v[126:127], v[126:127], v[166:167]
	v_pk_mul_f32 v[120:121], v[120:121], v[168:169]
	v_pk_mul_f32 v[122:123], v[122:123], v[170:171]
	v_pk_mul_f32 v[100:101], v[100:101], v[162:163] op_sel_hi:[1,0]
	v_pk_mul_f32 v[102:103], v[102:103], v[162:163] op_sel_hi:[1,0]
	v_mul_f32_e32 v176, 0xbfb8aa3b, v105
	v_pk_mul_f32 v[116:117], v[116:117], v[172:173]
	v_pk_mul_f32 v[118:119], v[118:119], v[174:175]
	v_pk_mul_f32 v[114:115], v[114:115], v[126:127]
	v_pk_mul_f32 v[112:113], v[112:113], v[124:125]
	v_pk_mul_f32 v[110:111], v[110:111], v[122:123]
	v_pk_mul_f32 v[108:109], v[108:109], v[120:121]
	v_pk_mul_f32 v[106:107], v[106:107], v[162:163] op_sel_hi:[1,0]
	v_exp_f32_e32 v176, v176
	v_pk_mul_f32 v[118:119], v[102:103], v[118:119]
	v_pk_mul_f32 v[116:117], v[100:101], v[116:117]
	v_cvt_pk_bf16_f32 v100, v112, v113
	v_cvt_pk_bf16_f32 v101, v114, v115
	v_cvt_pk_bf16_f32 v102, v108, v109
	v_cvt_pk_bf16_f32 v103, v110, v111
	global_store_dwordx4 v[158:159], v[100:103], off
	v_add_f32_e32 v187, 1.0, v176
	v_rcp_f32_e32 v176, v186
	v_mul_f32_e32 v100, 0xbfb8aa3b, v106
	v_mul_f32_e32 v101, 0xbfb8aa3b, v107
	v_exp_f32_e32 v100, v100
	v_exp_f32_e32 v101, v101
	v_rcp_f32_e32 v177, v187
	v_pk_mul_f32 v[96:97], v[96:97], v[162:163] op_sel_hi:[1,0]
	v_add_f32_e32 v100, 1.0, v100
	v_add_f32_e32 v101, 1.0, v101
	v_rcp_f32_e32 v100, v100
	v_rcp_f32_e32 v101, v101
	v_pk_mul_f32 v[102:103], v[104:105], v[176:177]
	ds_bpermute_b32 v104, v155, v163 offset:128
	v_pk_mul_f32 v[98:99], v[98:99], v[162:163] op_sel_hi:[1,0]
	v_pk_mul_f32 v[100:101], v[106:107], v[100:101]
	s_waitcnt lgkmcnt(0)
; __device__ __forceinline__ void store8(bf16_t* p, f32x4 a, f32x4 b) { u32x4 w; w.x = cvt_pk_bf16(a[0], a[1]); w.y = cvt_pk_bf16(a[2], a[3]); w.z = cvt_pk_bf16(b[0], b[1]); w.w = cvt_pk_bf16(b[2], b[3]); *(u32x4*)p = w; }
; __device__ __forceinline__ f32x4 sigmoid4(f32x4 x) { f32x4 r; r[0] = sigmoidf_(x[0]); r[1] = sigmoidf_(x[1]); r[2] = sigmoidf_(x[2]); r[3] = sigmoidf_(x[3]); return r; }
;     __device__ __forceinline__ void operator()(const f32x4 (&acc)[2][2][4][2], const Unit& u, int wr, int wc, int fr, int fq) const {
;     ...
;         for (int ai = 0; ai < 2; ++ai)
; #pragma unroll
;             for (int m = 0; m < 4; ++m) { const int row = row0 + ai * HALF + m * 16; const float rs = __shfl(rsl[ai], 16 * m + fr);
;                 f32x4 a[2];
; #pragma unroll
;                 for (int n = 0; n < 2; ++n) { const f32x4 g = acc[ai][0][m][n] * rs, up = acc[ai][1][m][n] * rs; a[n] = g * sigmoid4(g) * up; }
;                 store8(ACT + (size_t)row * 2816 + col0, a[0], a[1]); }
	v_pk_mul_f32 v[92:93], v[92:93], v[104:105] op_sel_hi:[1,0]
	v_pk_mul_f32 v[100:101], v[98:99], v[100:101]
	v_pk_mul_f32 v[98:99], v[96:97], v[102:103]
	v_or_b32_e32 v96, 16, v156
	v_mad_i64_i32 v[96:97], s[30:31], v96, s51, v[144:145]
	v_lshl_add_u64 v[102:103], v[96:97], 0, v[146:147]
	v_cvt_pk_bf16_f32 v96, v116, v117
	v_cvt_pk_bf16_f32 v97, v118, v119
	v_cvt_pk_bf16_f32 v98, v98, v99
	v_cvt_pk_bf16_f32 v99, v100, v101
	v_pk_mul_f32 v[94:95], v[94:95], v[104:105] op_sel_hi:[1,0]
	global_store_dwordx4 v[102:103], v[96:99], off
	v_pk_mul_f32 v[84:85], v[84:85], v[104:105] op_sel_hi:[1,0]
	v_pk_mul_f32 v[86:87], v[86:87], v[104:105] op_sel_hi:[1,0]
	v_mul_f32_e32 v96, 0xbfb8aa3b, v92
	v_mul_f32_e32 v97, 0xbfb8aa3b, v93
	v_mul_f32_e32 v98, 0xbfb8aa3b, v94
	v_mul_f32_e32 v99, 0xbfb8aa3b, v95
	v_exp_f32_e32 v96, v96
	v_exp_f32_e32 v97, v97
	v_exp_f32_e32 v98, v98
	v_exp_f32_e32 v99, v99
	v_add_f32_e32 v96, 1.0, v96
	v_add_f32_e32 v97, 1.0, v97
	v_add_f32_e32 v98, 1.0, v98
	v_add_f32_e32 v99, 1.0, v99
	v_rcp_f32_e32 v96, v96
	v_rcp_f32_e32 v97, v97
	v_rcp_f32_e32 v98, v98
	v_rcp_f32_e32 v99, v99
	v_pk_mul_f32 v[88:89], v[88:89], v[104:105] op_sel_hi:[1,0]
	v_pk_mul_f32 v[92:93], v[92:93], v[96:97]
	v_pk_mul_f32 v[90:91], v[90:91], v[104:105] op_sel_hi:[1,0]
	v_pk_mul_f32 v[94:95], v[94:95], v[98:99]
	v_pk_mul_f32 v[84:85], v[84:85], v[92:93]
	v_pk_mul_f32 v[86:87], v[86:87], v[94:95]
	v_mul_f32_e32 v92, 0xbfb8aa3b, v88
	v_mul_f32_e32 v93, 0xbfb8aa3b, v89
	v_mul_f32_e32 v94, 0xbfb8aa3b, v90
	v_mul_f32_e32 v95, 0xbfb8aa3b, v91
	v_exp_f32_e32 v92, v92
	v_exp_f32_e32 v93, v93
	v_exp_f32_e32 v94, v94
	v_exp_f32_e32 v95, v95
	v_add_f32_e32 v92, 1.0, v92
	v_add_f32_e32 v93, 1.0, v93
	v_add_f32_e32 v94, 1.0, v94
	v_add_f32_e32 v95, 1.0, v95
	v_rcp_f32_e32 v92, v92
	v_rcp_f32_e32 v93, v93
	v_rcp_f32_e32 v94, v94
	v_rcp_f32_e32 v95, v95
	v_pk_mul_f32 v[80:81], v[80:81], v[104:105] op_sel_hi:[1,0]
	v_pk_mul_f32 v[82:83], v[82:83], v[104:105] op_sel_hi:[1,0]
	v_pk_mul_f32 v[88:89], v[88:89], v[92:93]
	v_pk_mul_f32 v[90:91], v[90:91], v[94:95]
	s_nop 0
	v_pk_mul_f32 v[90:91], v[82:83], v[90:91]
	v_pk_mul_f32 v[82:83], v[80:81], v[88:89]
	v_or_b32_e32 v80, 32, v156
	v_mad_i64_i32 v[80:81], s[30:31], v80, s51, v[144:145]
	v_lshl_add_u64 v[88:89], v[80:81], 0, v[146:147]
	v_cvt_pk_bf16_f32 v80, v84, v85
	ds_bpermute_b32 v84, v155, v163 offset:192
	v_cvt_pk_bf16_f32 v81, v86, v87
	v_cvt_pk_bf16_f32 v82, v82, v83
	v_cvt_pk_bf16_f32 v83, v90, v91
	global_store_dwordx4 v[88:89], v[80:83], off
	s_waitcnt lgkmcnt(0)
	v_pk_mul_f32 v[76:77], v[76:77], v[84:85] op_sel_hi:[1,0]
	v_pk_mul_f32 v[78:79], v[78:79], v[84:85] op_sel_hi:[1,0]
	v_mul_f32_e32 v80, 0xbfb8aa3b, v76
	v_mul_f32_e32 v81, 0xbfb8aa3b, v77
	v_mul_f32_e32 v82, 0xbfb8aa3b, v78
	v_mul_f32_e32 v83, 0xbfb8aa3b, v79
	v_exp_f32_e32 v80, v80
	v_exp_f32_e32 v81, v81
	v_exp_f32_e32 v82, v82
	v_exp_f32_e32 v83, v83
	v_add_f32_e32 v80, 1.0, v80
	v_add_f32_e32 v81, 1.0, v81
	v_add_f32_e32 v82, 1.0, v82
	v_add_f32_e32 v83, 1.0, v83
	v_rcp_f32_e32 v80, v80
	v_rcp_f32_e32 v81, v81
	v_rcp_f32_e32 v82, v82
	v_rcp_f32_e32 v83, v83
	v_pk_mul_f32 v[68:69], v[68:69], v[84:85] op_sel_hi:[1,0]
	v_pk_mul_f32 v[70:71], v[70:71], v[84:85] op_sel_hi:[1,0]
	v_pk_mul_f32 v[76:77], v[76:77], v[80:81]
	v_pk_mul_f32 v[78:79], v[78:79], v[82:83]
	v_pk_mul_f32 v[72:73], v[72:73], v[84:85] op_sel_hi:[1,0]
	v_pk_mul_f32 v[74:75], v[74:75], v[84:85] op_sel_hi:[1,0]
	v_pk_mul_f32 v[70:71], v[70:71], v[78:79]
	v_pk_mul_f32 v[68:69], v[68:69], v[76:77]
	v_mul_f32_e32 v76, 0xbfb8aa3b, v72
	v_mul_f32_e32 v77, 0xbfb8aa3b, v73
	v_mul_f32_e32 v78, 0xbfb8aa3b, v74
	v_mul_f32_e32 v79, 0xbfb8aa3b, v75
	v_exp_f32_e32 v76, v76
	v_exp_f32_e32 v77, v77
	v_exp_f32_e32 v78, v78
	v_exp_f32_e32 v79, v79
	v_add_f32_e32 v76, 1.0, v76
	v_add_f32_e32 v77, 1.0, v77
	v_add_f32_e32 v78, 1.0, v78
	v_add_f32_e32 v79, 1.0, v79
	v_rcp_f32_e32 v76, v76
	v_rcp_f32_e32 v77, v77
	v_rcp_f32_e32 v78, v78
	v_rcp_f32_e32 v79, v79
	v_pk_mul_f32 v[64:65], v[64:65], v[84:85] op_sel_hi:[1,0]
	v_pk_mul_f32 v[66:67], v[66:67], v[84:85] op_sel_hi:[1,0]
	v_pk_mul_f32 v[72:73], v[72:73], v[76:77]
	v_pk_mul_f32 v[74:75], v[74:75], v[78:79]
	s_nop 0
	v_pk_mul_f32 v[74:75], v[66:67], v[74:75]
	v_pk_mul_f32 v[66:67], v[64:65], v[72:73]
	v_or_b32_e32 v64, 48, v156
	v_mad_i64_i32 v[64:65], s[30:31], v64, s51, v[144:145]
	v_lshl_add_u64 v[72:73], v[64:65], 0, v[146:147]
	v_cvt_pk_bf16_f32 v64, v68, v69
	ds_bpermute_b32 v68, v155, v157
	v_add_u32_e32 v69, 0x80, v156
	v_cvt_pk_bf16_f32 v65, v70, v71
	v_cvt_pk_bf16_f32 v66, v66, v67
	v_cvt_pk_bf16_f32 v67, v74, v75
	s_waitcnt lgkmcnt(0)
; __device__ __forceinline__ void store8(bf16_t* p, f32x4 a, f32x4 b) { u32x4 w; w.x = cvt_pk_bf16(a[0], a[1]); w.y = cvt_pk_bf16(a[2], a[3]); w.z = cvt_pk_bf16(b[0], b[1]); w.w = cvt_pk_bf16(b[2], b[3]); *(u32x4*)p = w; }
; __device__ __forceinline__ f32x4 sigmoid4(f32x4 x) { f32x4 r; r[0] = sigmoidf_(x[0]); r[1] = sigmoidf_(x[1]); r[2] = sigmoidf_(x[2]); r[3] = sigmoidf_(x[3]); return r; }
;     __device__ __forceinline__ void operator()(const f32x4 (&acc)[2][2][4][2], const Unit& u, int wr, int wc, int fr, int fq) const {
;     ...
;         for (int ai = 0; ai < 2; ++ai)
; #pragma unroll
;             for (int m = 0; m < 4; ++m) { const int row = row0 + ai * HALF + m * 16; const float rs = __shfl(rsl[ai], 16 * m + fr);
;                 f32x4 a[2];
; #pragma unroll
;                 for (int n = 0; n < 2; ++n) { const f32x4 g = acc[ai][0][m][n] * rs, up = acc[ai][1][m][n] * rs; a[n] = g * sigmoid4(g) * up; }
;                 store8(ACT + (size_t)row * 2816 + col0, a[0], a[1]); }
	v_pk_mul_f32 v[60:61], v[60:61], v[68:69] op_sel_hi:[1,0]
	v_pk_mul_f32 v[62:63], v[62:63], v[68:69] op_sel_hi:[1,0]
	global_store_dwordx4 v[72:73], v[64:67], off
	v_pk_mul_f32 v[52:53], v[52:53], v[68:69] op_sel_hi:[1,0]
	v_pk_mul_f32 v[54:55], v[54:55], v[68:69] op_sel_hi:[1,0]
	v_mul_f32_e32 v64, 0xbfb8aa3b, v60
	v_mul_f32_e32 v65, 0xbfb8aa3b, v61
	v_mul_f32_e32 v66, 0xbfb8aa3b, v62
	v_mul_f32_e32 v67, 0xbfb8aa3b, v63
	v_exp_f32_e32 v64, v64
	v_exp_f32_e32 v65, v65
	v_exp_f32_e32 v66, v66
	v_exp_f32_e32 v67, v67
	v_add_f32_e32 v64, 1.0, v64
	v_add_f32_e32 v65, 1.0, v65
	v_add_f32_e32 v66, 1.0, v66
	v_add_f32_e32 v67, 1.0, v67
	v_rcp_f32_e32 v64, v64
	v_rcp_f32_e32 v65, v65
	v_rcp_f32_e32 v66, v66
	v_rcp_f32_e32 v67, v67
	v_pk_mul_f32 v[56:57], v[56:57], v[68:69] op_sel_hi:[1,0]
	v_pk_mul_f32 v[60:61], v[60:61], v[64:65]
	v_pk_mul_f32 v[58:59], v[58:59], v[68:69] op_sel_hi:[1,0]
	v_pk_mul_f32 v[62:63], v[62:63], v[66:67]
	v_pk_mul_f32 v[52:53], v[52:53], v[60:61]
	v_pk_mul_f32 v[54:55], v[54:55], v[62:63]
	v_mul_f32_e32 v60, 0xbfb8aa3b, v56
	v_mul_f32_e32 v61, 0xbfb8aa3b, v57
	v_mul_f32_e32 v62, 0xbfb8aa3b, v58
	v_mul_f32_e32 v63, 0xbfb8aa3b, v59
	v_exp_f32_e32 v60, v60
	v_exp_f32_e32 v61, v61
	v_exp_f32_e32 v62, v62
	v_exp_f32_e32 v63, v63
	v_add_f32_e32 v60, 1.0, v60
	v_add_f32_e32 v61, 1.0, v61
	v_add_f32_e32 v62, 1.0, v62
	v_add_f32_e32 v63, 1.0, v63
	v_rcp_f32_e32 v60, v60
	v_rcp_f32_e32 v61, v61
	v_rcp_f32_e32 v62, v62
	v_rcp_f32_e32 v63, v63
	v_pk_mul_f32 v[48:49], v[48:49], v[68:69] op_sel_hi:[1,0]
	v_pk_mul_f32 v[50:51], v[50:51], v[68:69] op_sel_hi:[1,0]
	v_pk_mul_f32 v[56:57], v[56:57], v[60:61]
	v_pk_mul_f32 v[58:59], v[58:59], v[62:63]
	s_nop 0
	v_pk_mul_f32 v[58:59], v[50:51], v[58:59]
	v_pk_mul_f32 v[50:51], v[48:49], v[56:57]
	v_mad_i64_i32 v[48:49], s[30:31], v69, s51, v[144:145]
	v_lshl_add_u64 v[56:57], v[48:49], 0, v[146:147]
	v_cvt_pk_bf16_f32 v48, v52, v53
	ds_bpermute_b32 v52, v155, v157 offset:64
	v_cvt_pk_bf16_f32 v49, v54, v55
	v_cvt_pk_bf16_f32 v50, v50, v51
	v_cvt_pk_bf16_f32 v51, v58, v59
	global_store_dwordx4 v[56:57], v[48:51], off
	s_waitcnt lgkmcnt(0)
	v_pk_mul_f32 v[44:45], v[44:45], v[52:53] op_sel_hi:[1,0]
	v_pk_mul_f32 v[46:47], v[46:47], v[52:53] op_sel_hi:[1,0]
	v_mul_f32_e32 v48, 0xbfb8aa3b, v44
	v_mul_f32_e32 v49, 0xbfb8aa3b, v45
	v_mul_f32_e32 v50, 0xbfb8aa3b, v46
	v_mul_f32_e32 v51, 0xbfb8aa3b, v47
	v_exp_f32_e32 v48, v48
	v_exp_f32_e32 v49, v49
	v_exp_f32_e32 v50, v50
	v_exp_f32_e32 v51, v51
	v_add_f32_e32 v48, 1.0, v48
	v_add_f32_e32 v49, 1.0, v49
	v_add_f32_e32 v50, 1.0, v50
	v_add_f32_e32 v51, 1.0, v51
	v_rcp_f32_e32 v48, v48
	v_rcp_f32_e32 v49, v49
	v_rcp_f32_e32 v50, v50
	v_rcp_f32_e32 v51, v51
	v_pk_mul_f32 v[36:37], v[36:37], v[52:53] op_sel_hi:[1,0]
	v_pk_mul_f32 v[38:39], v[38:39], v[52:53] op_sel_hi:[1,0]
	v_pk_mul_f32 v[44:45], v[44:45], v[48:49]
	v_pk_mul_f32 v[46:47], v[46:47], v[50:51]
	v_pk_mul_f32 v[40:41], v[40:41], v[52:53] op_sel_hi:[1,0]
	v_pk_mul_f32 v[42:43], v[42:43], v[52:53] op_sel_hi:[1,0]
	v_pk_mul_f32 v[38:39], v[38:39], v[46:47]
	v_pk_mul_f32 v[36:37], v[36:37], v[44:45]
	v_mul_f32_e32 v44, 0xbfb8aa3b, v40
	v_mul_f32_e32 v45, 0xbfb8aa3b, v41
	v_mul_f32_e32 v46, 0xbfb8aa3b, v42
	v_mul_f32_e32 v47, 0xbfb8aa3b, v43
	v_exp_f32_e32 v44, v44
	v_exp_f32_e32 v45, v45
	v_exp_f32_e32 v46, v46
	v_exp_f32_e32 v47, v47
	v_add_f32_e32 v44, 1.0, v44
	v_add_f32_e32 v45, 1.0, v45
	v_add_f32_e32 v46, 1.0, v46
	v_add_f32_e32 v47, 1.0, v47
	v_rcp_f32_e32 v44, v44
	v_rcp_f32_e32 v45, v45
	v_rcp_f32_e32 v46, v46
	v_rcp_f32_e32 v47, v47
	v_pk_mul_f32 v[32:33], v[32:33], v[52:53] op_sel_hi:[1,0]
	v_pk_mul_f32 v[34:35], v[34:35], v[52:53] op_sel_hi:[1,0]
	v_pk_mul_f32 v[40:41], v[40:41], v[44:45]
	v_pk_mul_f32 v[42:43], v[42:43], v[46:47]
	s_nop 0
	v_pk_mul_f32 v[42:43], v[34:35], v[42:43]
	v_pk_mul_f32 v[34:35], v[32:33], v[40:41]
	v_add_u32_e32 v32, 0x90, v156
	v_mad_i64_i32 v[32:33], s[30:31], v32, s51, v[144:145]
	v_lshl_add_u64 v[40:41], v[32:33], 0, v[146:147]
	v_cvt_pk_bf16_f32 v32, v36, v37
	ds_bpermute_b32 v36, v155, v157 offset:128
	v_cvt_pk_bf16_f32 v33, v38, v39
	v_cvt_pk_bf16_f32 v34, v34, v35
	v_cvt_pk_bf16_f32 v35, v42, v43
	global_store_dwordx4 v[40:41], v[32:35], off
	s_waitcnt lgkmcnt(0)
; __device__ __forceinline__ void store8(bf16_t* p, f32x4 a, f32x4 b) { u32x4 w; w.x = cvt_pk_bf16(a[0], a[1]); w.y = cvt_pk_bf16(a[2], a[3]); w.z = cvt_pk_bf16(b[0], b[1]); w.w = cvt_pk_bf16(b[2], b[3]); *(u32x4*)p = w; }
; __device__ __forceinline__ f32x4 sigmoid4(f32x4 x) { f32x4 r; r[0] = sigmoidf_(x[0]); r[1] = sigmoidf_(x[1]); r[2] = sigmoidf_(x[2]); r[3] = sigmoidf_(x[3]); return r; }
; #define PG8_BAR __builtin_amdgcn_s_barrier()
;     __device__ __forceinline__ void operator()(const f32x4 (&acc)[2][2][4][2], const Unit& u, int wr, int wc, int fr, int fq) const {
;     ...
;         for (int ai = 0; ai < 2; ++ai)
; #pragma unroll
;             for (int m = 0; m < 4; ++m) { const int row = row0 + ai * HALF + m * 16; const float rs = __shfl(rsl[ai], 16 * m + fr);
;                 f32x4 a[2];
; #pragma unroll
;                 for (int n = 0; n < 2; ++n) { const f32x4 g = acc[ai][0][m][n] * rs, up = acc[ai][1][m][n] * rs; a[n] = g * sigmoid4(g) * up; }
;                 store8(ACT + (size_t)row * 2816 + col0, a[0], a[1]); }
; template <class Epi, class Sched, bool ALIGN_EPI = false, bool SP2 = false>
; __device__ __forceinline__ void gemm_phase(PG8_LAS unsigned char* lds, const Gemm g, const Sched& S, const Epi& E) {
;     ...
;         if (!has_next) break;
;         if (!(Epi::KEEP && cur.seg == 0)) {
; #pragma unroll
;         for (int a = 0; a < 2; ++a)
; #pragma unroll
;             for (int b = 0; b < 2; ++b)
; #pragma unroll
;                 for (int m = 0; m < 4; ++m)
; #pragma unroll
;                     for (int n = 0; n < 2; ++n) acc[a][b][m][n] = (f32x4){0.f, 0.f, 0.f, 0.f};
;         }
;         cur = nxt; cA = nA; cB = nB; ++ui;
;         if constexpr (ALIGN_EPI) { if (wr == 1) PG8_BAR; }
	v_pk_mul_f32 v[28:29], v[28:29], v[36:37] op_sel_hi:[1,0]
	v_pk_mul_f32 v[30:31], v[30:31], v[36:37] op_sel_hi:[1,0]
	v_mul_f32_e32 v32, 0xbfb8aa3b, v28
	v_mul_f32_e32 v33, 0xbfb8aa3b, v29
	v_mul_f32_e32 v34, 0xbfb8aa3b, v30
	v_mul_f32_e32 v35, 0xbfb8aa3b, v31
	v_exp_f32_e32 v32, v32
	v_exp_f32_e32 v33, v33
	v_exp_f32_e32 v34, v34
	v_exp_f32_e32 v35, v35
	v_add_f32_e32 v32, 1.0, v32
	v_add_f32_e32 v33, 1.0, v33
	v_add_f32_e32 v34, 1.0, v34
	v_add_f32_e32 v35, 1.0, v35
	v_rcp_f32_e32 v32, v32
	v_rcp_f32_e32 v33, v33
	v_rcp_f32_e32 v34, v34
	v_rcp_f32_e32 v35, v35
	v_pk_mul_f32 v[20:21], v[20:21], v[36:37] op_sel_hi:[1,0]
	v_pk_mul_f32 v[22:23], v[22:23], v[36:37] op_sel_hi:[1,0]
	v_pk_mul_f32 v[28:29], v[28:29], v[32:33]
	v_pk_mul_f32 v[30:31], v[30:31], v[34:35]
	v_pk_mul_f32 v[24:25], v[24:25], v[36:37] op_sel_hi:[1,0]
	v_pk_mul_f32 v[26:27], v[26:27], v[36:37] op_sel_hi:[1,0]
	v_pk_mul_f32 v[22:23], v[22:23], v[30:31]
	v_pk_mul_f32 v[20:21], v[20:21], v[28:29]
	v_mul_f32_e32 v28, 0xbfb8aa3b, v24
	v_mul_f32_e32 v29, 0xbfb8aa3b, v25
	v_mul_f32_e32 v30, 0xbfb8aa3b, v26
	v_mul_f32_e32 v31, 0xbfb8aa3b, v27
	v_exp_f32_e32 v28, v28
	v_exp_f32_e32 v29, v29
	v_exp_f32_e32 v30, v30
	v_exp_f32_e32 v31, v31
	v_add_f32_e32 v28, 1.0, v28
	v_add_f32_e32 v29, 1.0, v29
	v_add_f32_e32 v30, 1.0, v30
	v_add_f32_e32 v31, 1.0, v31
	v_rcp_f32_e32 v28, v28
	v_rcp_f32_e32 v29, v29
	v_rcp_f32_e32 v30, v30
	v_rcp_f32_e32 v31, v31
	v_pk_mul_f32 v[16:17], v[16:17], v[36:37] op_sel_hi:[1,0]
	v_pk_mul_f32 v[18:19], v[18:19], v[36:37] op_sel_hi:[1,0]
	v_pk_mul_f32 v[24:25], v[24:25], v[28:29]
	v_pk_mul_f32 v[26:27], v[26:27], v[30:31]
	s_nop 0
	v_pk_mul_f32 v[26:27], v[18:19], v[26:27]
	v_pk_mul_f32 v[18:19], v[16:17], v[24:25]
	v_add_u32_e32 v16, 0xa0, v156
	v_mad_i64_i32 v[16:17], s[30:31], v16, s51, v[144:145]
	v_lshl_add_u64 v[24:25], v[16:17], 0, v[146:147]
	v_cvt_pk_bf16_f32 v16, v20, v21
	ds_bpermute_b32 v20, v155, v157 offset:192
	v_cvt_pk_bf16_f32 v17, v22, v23
	v_cvt_pk_bf16_f32 v18, v18, v19
	v_cvt_pk_bf16_f32 v19, v26, v27
	global_store_dwordx4 v[24:25], v[16:19], off
	s_waitcnt lgkmcnt(0)
	v_pk_mul_f32 v[12:13], v[12:13], v[20:21] op_sel_hi:[1,0]
	v_pk_mul_f32 v[14:15], v[14:15], v[20:21] op_sel_hi:[1,0]
	v_mul_f32_e32 v16, 0xbfb8aa3b, v12
	v_mul_f32_e32 v17, 0xbfb8aa3b, v13
	v_mul_f32_e32 v18, 0xbfb8aa3b, v14
	v_mul_f32_e32 v19, 0xbfb8aa3b, v15
	v_exp_f32_e32 v16, v16
	v_exp_f32_e32 v17, v17
	v_exp_f32_e32 v18, v18
	v_exp_f32_e32 v19, v19
	v_add_f32_e32 v16, 1.0, v16
	v_add_f32_e32 v17, 1.0, v17
	v_add_f32_e32 v18, 1.0, v18
	v_add_f32_e32 v19, 1.0, v19
	v_rcp_f32_e32 v16, v16
	v_rcp_f32_e32 v17, v17
	v_rcp_f32_e32 v18, v18
	v_rcp_f32_e32 v19, v19
	v_pk_mul_f32 v[4:5], v[4:5], v[20:21] op_sel_hi:[1,0]
	v_pk_mul_f32 v[6:7], v[6:7], v[20:21] op_sel_hi:[1,0]
	v_pk_mul_f32 v[12:13], v[12:13], v[16:17]
	v_pk_mul_f32 v[14:15], v[14:15], v[18:19]
	v_pk_mul_f32 v[8:9], v[8:9], v[20:21] op_sel_hi:[1,0]
	v_pk_mul_f32 v[10:11], v[10:11], v[20:21] op_sel_hi:[1,0]
	v_pk_mul_f32 v[6:7], v[6:7], v[14:15]
	v_pk_mul_f32 v[4:5], v[4:5], v[12:13]
	v_mul_f32_e32 v12, 0xbfb8aa3b, v8
	v_mul_f32_e32 v13, 0xbfb8aa3b, v9
	v_mul_f32_e32 v14, 0xbfb8aa3b, v10
	v_mul_f32_e32 v15, 0xbfb8aa3b, v11
	v_exp_f32_e32 v12, v12
	v_exp_f32_e32 v13, v13
	v_exp_f32_e32 v14, v14
	v_exp_f32_e32 v15, v15
	v_add_f32_e32 v12, 1.0, v12
	v_add_f32_e32 v13, 1.0, v13
	v_add_f32_e32 v14, 1.0, v14
	v_add_f32_e32 v15, 1.0, v15
	v_rcp_f32_e32 v12, v12
	v_rcp_f32_e32 v13, v13
	v_rcp_f32_e32 v14, v14
	v_rcp_f32_e32 v15, v15
	v_pk_mul_f32 v[0:1], v[0:1], v[20:21] op_sel_hi:[1,0]
	v_pk_mul_f32 v[2:3], v[2:3], v[20:21] op_sel_hi:[1,0]
	v_pk_mul_f32 v[8:9], v[8:9], v[12:13]
	v_pk_mul_f32 v[10:11], v[10:11], v[14:15]
	s_nop 0
	v_pk_mul_f32 v[10:11], v[2:3], v[10:11]
	v_pk_mul_f32 v[2:3], v[0:1], v[8:9]
	v_add_u32_e32 v0, 0xb0, v156
	v_mad_i64_i32 v[0:1], s[30:31], v0, s51, v[144:145]
	v_lshl_add_u64 v[8:9], v[0:1], 0, v[146:147]
	v_cvt_pk_bf16_f32 v0, v4, v5
	v_cvt_pk_bf16_f32 v1, v6, v7
	v_cvt_pk_bf16_f32 v2, v2, v3
	v_cvt_pk_bf16_f32 v3, v10, v11
	global_store_dwordx4 v[8:9], v[0:3], off
	s_mov_b32 s66, 1
	s_cbranch_vccnz .LBB0_767
	s_andn2_b64 vcc, exec, s[14:15]
	s_cbranch_vccnz .LBB0_766
	s_barrier
	s_branch .LBB0_766
